# row-rms loops: prefetch depth 2 (two spare register sets, body unrolled x2, counted vmcnt(24) in steady state)
# baseline (speedup 1.0000x reference)
.LBB0_128:
	s_cmp_lg_u32 s70, 1
	s_cbranch_scc1 .LBB0_185
	v_mov_b32_e32 v0, v212
	v_readlane_b32 s6, v254, 9
	v_readlane_b32 s7, v254, 10
	v_readfirstlane_b32 s4, v0
	v_readlane_b32 s5, v254, 0
	s_ashr_i32 s4, s4, 6
	s_lshl_b32 s7, s5, 3
	s_add_i32 s7, s7, s4
	s_mov_b64 s[4:5], 0
	s_cmpk_gt_i32 s7, 0x3fff
	s_cbranch_scc1 .LBB0_132
	v_readlane_b32 s12, v254, 13
	s_mul_i32 s8, s68, 0x3000
	v_readlane_b32 s16, v254, 17
	v_and_b32_e32 v18, 63, v0
	s_mul_hi_i32 s9, s68, 0x3000
	v_readlane_b32 s17, v254, 18
	s_add_u32 s8, s16, s8
	s_addc_u32 s9, s17, s9
	v_lshlrev_b32_e32 v0, 4, v18
	v_lshl_add_u64 v[2:3], s[8:9], 0, v[0:1]
	s_mov_b64 s[8:9], 0x2000
	v_add_co_u32_e32 v10, vcc, 0x2000, v2
	v_lshl_add_u64 v[14:15], v[2:3], 0, s[8:9]
	s_nop 0
	v_addc_co_u32_e32 v11, vcc, 0, v3, vcc
	global_load_dwordx4 v[2:5], v[14:15], off offset:1024
	global_load_dwordx4 v[6:9], v[14:15], off offset:2048
	s_nop 0
	global_load_dwordx4 v[10:13], v[10:11], off
	s_nop 0
	global_load_dwordx4 v[14:17], v[14:15], off offset:3072
	s_lshl_b32 s8, s7, 1
	s_ashr_i32 s9, s8, 31
	s_lshl_b32 s6, s6, 4
	s_lshl_b64 s[10:11], s[8:9], 11
	s_add_u32 s4, s4, s10
	s_addc_u32 s5, s5, s11
	v_readlane_b32 s7, v255, 11
	s_add_u32 s4, s7, s4
	v_readlane_b32 s7, v255, 12
	v_lshlrev_b32_e32 v18, 3, v18
	v_mov_b32_e32 v19, v1
	s_addc_u32 s5, s7, s5
	s_ashr_i32 s7, s6, 31
	v_lshl_add_u64 v[50:51], s[4:5], 0, v[18:19]
	s_lshl_b64 s[10:11], s[6:7], 11
	s_lshl_b64 s[4:5], s[8:9], 12
	v_readlane_b32 s9, v255, 13
	s_add_u32 s4, s9, s4
	v_readlane_b32 s9, v255, 14
	v_readlane_b32 s13, v254, 14
	s_addc_u32 s5, s9, s5
	v_lshl_add_u64 v[52:53], s[4:5], 0, v[0:1]
	s_lshl_b64 s[12:13], s[6:7], 12
	v_readlane_b32 s14, v254, 15
	v_readlane_b32 s15, v254, 16
	v_readlane_b32 s18, v254, 19
	v_readlane_b32 s19, v254, 20
	v_readlane_b32 s20, v254, 21
	v_readlane_b32 s21, v254, 22
	v_readlane_b32 s22, v254, 23
	v_readlane_b32 s23, v254, 24
	v_readlane_b32 s24, v254, 25
	v_readlane_b32 s25, v254, 26
	v_readlane_b32 s26, v254, 27
	v_readlane_b32 s27, v254, 28
	global_load_dwordx4 v[116:119], v[52:53], off offset:-4096
	global_load_dwordx4 v[112:115], v[52:53], off offset:-3072
	global_load_dwordx4 v[104:107], v[52:53], off offset:-1024
	global_load_dwordx4 v[108:111], v[52:53], off offset:-2048
	global_load_dwordx4 v[100:103], v[52:53], off
	global_load_dwordx4 v[96:99], v[52:53], off offset:1024
	global_load_dwordx4 v[88:91], v[52:53], off offset:3072
	global_load_dwordx4 v[92:95], v[52:53], off offset:2048
	v_lshl_add_u64 v[52:53], v[52:53], 0, s[12:13]
	s_mov_b32 s29, 0
	s_add_i32 s28, s8, s6
	s_cmp_lt_i32 s28, 0x8000
	s_cbranch_scc0 .Lrms2_p_a
	global_load_dwordx4 v[192:195], v[52:53], off offset:-4096
	global_load_dwordx4 v[188:191], v[52:53], off offset:-3072
	global_load_dwordx4 v[180:183], v[52:53], off offset:-1024
	global_load_dwordx4 v[184:187], v[52:53], off offset:-2048
	global_load_dwordx4 v[176:179], v[52:53], off
	global_load_dwordx4 v[172:175], v[52:53], off offset:1024
	global_load_dwordx4 v[164:167], v[52:53], off offset:3072
	global_load_dwordx4 v[168:171], v[52:53], off offset:2048
	v_lshl_add_u64 v[52:53], v[52:53], 0, s[12:13]
.Lrms2_p_a:
.LBB0_131:
	s_add_i32 s28, s8, s6
	s_cmp_lt_i32 s28, 0x8000
	s_cbranch_scc0 .Lrms2_w0_ae
	s_cmp_lt_u32 s29, 2
	s_cbranch_scc1 .Lrms2_w0_ae
	s_waitcnt vmcnt(24)
	s_branch .Lrms2_go_ae

.Lrms2_go_ae:
	v_mov_b64_e32 v[18:19], v[88:89]
	v_mov_b64_e32 v[20:21], v[90:91]
	v_mov_b64_e32 v[22:23], v[92:93]
	v_mov_b64_e32 v[24:25], v[94:95]
	v_mov_b64_e32 v[26:27], v[96:97]
	v_mov_b64_e32 v[28:29], v[98:99]
	v_mov_b64_e32 v[30:31], v[100:101]
	v_mov_b64_e32 v[32:33], v[102:103]
	v_mov_b64_e32 v[34:35], v[104:105]
	v_mov_b64_e32 v[36:37], v[106:107]
	v_mov_b64_e32 v[38:39], v[108:109]
	v_mov_b64_e32 v[40:41], v[110:111]
	v_mov_b64_e32 v[42:43], v[112:113]
	v_mov_b64_e32 v[44:45], v[114:115]
	v_mov_b64_e32 v[46:47], v[116:117]
	v_mov_b64_e32 v[48:49], v[118:119]
	s_add_i32 s29, s29, 1
	s_add_i32 s28, s28, s6
	s_cmp_lt_i32 s28, 0x8000
	s_cbranch_scc0 .Lrms2_n_ae
	global_load_dwordx4 v[116:119], v[52:53], off offset:-4096
	global_load_dwordx4 v[112:115], v[52:53], off offset:-3072
	global_load_dwordx4 v[104:107], v[52:53], off offset:-1024
	global_load_dwordx4 v[108:111], v[52:53], off offset:-2048
	global_load_dwordx4 v[100:103], v[52:53], off
	global_load_dwordx4 v[96:99], v[52:53], off offset:1024
	global_load_dwordx4 v[88:91], v[52:53], off offset:3072
	global_load_dwordx4 v[92:95], v[52:53], off offset:2048
	v_lshl_add_u64 v[52:53], v[52:53], 0, s[12:13]
.Lrms2_n_ae:
	v_pk_mul_f32 v[54:55], v[48:49], v[48:49]
	v_pk_mul_f32 v[56:57], v[46:47], v[46:47]
	v_pk_mul_f32 v[58:59], v[44:45], v[44:45]
	v_pk_mul_f32 v[60:61], v[42:43], v[42:43]
	v_mul_f32_e32 v0, v39, v39
	v_mul_f32_e32 v62, v41, v41
	v_pk_mul_f32 v[64:65], v[32:33], v[32:33]
	v_pk_mul_f32 v[66:67], v[30:31], v[30:31]
	v_pk_mul_f32 v[68:69], v[28:29], v[28:29]
	v_pk_mul_f32 v[70:71], v[26:27], v[26:27]
	v_mul_f32_e32 v81, v36, v36
	v_mul_f32_e32 v82, v37, v37
	v_pk_mov_b32 v[76:77], v[56:57], v[54:55] op_sel:[1,0]
	v_mov_b32_e32 v57, v55
	v_pk_mov_b32 v[54:55], v[60:61], v[58:59] op_sel:[1,0]
	v_mov_b32_e32 v61, v59
	v_pk_fma_f32 v[58:59], v[38:39], v[38:39], v[0:1] op_sel_hi:[1,1,0]
	v_pk_fma_f32 v[62:63], v[40:41], v[40:41], v[62:63] op_sel_hi:[1,1,0]
	v_pk_mov_b32 v[78:79], v[66:67], v[64:65] op_sel:[1,0]
	v_mov_b32_e32 v67, v65
	v_pk_mov_b32 v[64:65], v[70:71], v[68:69] op_sel:[1,0]
	v_mov_b32_e32 v71, v69
	v_mul_f32_e32 v75, v34, v34
	v_mul_f32_e32 v72, v23, v23
	v_mul_f32_e32 v74, v25, v25
	v_pk_add_f32 v[56:57], v[76:77], v[56:57]
	v_pk_add_f32 v[54:55], v[54:55], v[60:61]
	v_mov_b32_e32 v59, v81
	v_mov_b32_e32 v63, v82
	v_pk_add_f32 v[60:61], v[78:79], v[66:67]
	v_pk_add_f32 v[64:65], v[64:65], v[70:71]
	v_mul_f32_e32 v80, v35, v35
	v_mul_f32_e32 v83, v18, v18
	v_mul_f32_e32 v84, v19, v19
	v_mul_f32_e32 v85, v20, v20
	v_mul_f32_e32 v86, v21, v21
	v_pk_fma_f32 v[68:69], v[22:23], v[22:23], v[72:73] op_sel_hi:[1,1,0]
	v_pk_fma_f32 v[72:73], v[24:25], v[24:25], v[74:75] op_sel_hi:[1,1,0]
	v_pk_add_f32 v[56:57], v[56:57], v[56:57] op_sel:[0,1] op_sel_hi:[1,0]
	v_pk_add_f32 v[54:55], v[54:55], v[54:55] op_sel:[0,1] op_sel_hi:[1,0]
	v_pk_add_f32 v[58:59], v[58:59], v[62:63]
	v_pk_add_f32 v[60:61], v[60:61], v[60:61] op_sel:[0,1] op_sel_hi:[1,0]
	v_pk_add_f32 v[62:63], v[64:65], v[64:65] op_sel:[0,1] op_sel_hi:[1,0]
	v_mov_b32_e32 v69, v85
	v_mov_b32_e32 v73, v86
	v_mov_b32_e32 v57, v75
	v_mov_b32_e32 v55, v80
	v_mov_b32_e32 v61, v83
	v_mov_b32_e32 v63, v84
	v_pk_add_f32 v[64:65], v[68:69], v[72:73]
	v_pk_add_f32 v[54:55], v[56:57], v[54:55]
	v_pk_add_f32 v[56:57], v[60:61], v[62:63]
	v_pk_add_f32 v[54:55], v[54:55], v[58:59]
	v_pk_add_f32 v[56:57], v[56:57], v[64:65]
	v_add_f32_e32 v0, v54, v55
	v_add_f32_e32 v54, v56, v57
	s_nop 0
	v_add_f32_dpp v0, v0, v0 row_ror:8 row_mask:0xf bank_mask:0xf bound_ctrl:1
	v_add_f32_dpp v54, v54, v54 row_ror:8 row_mask:0xf bank_mask:0xf bound_ctrl:1
	s_nop 0
	v_add_f32_dpp v0, v0, v0 row_ror:4 row_mask:0xf bank_mask:0xf bound_ctrl:1
	v_add_f32_dpp v54, v54, v54 row_ror:4 row_mask:0xf bank_mask:0xf bound_ctrl:1
	s_nop 0
	v_add_f32_dpp v0, v0, v0 row_ror:2 row_mask:0xf bank_mask:0xf bound_ctrl:1
	v_add_f32_dpp v54, v54, v54 row_ror:2 row_mask:0xf bank_mask:0xf bound_ctrl:1
	s_nop 0
	v_add_f32_dpp v0, v0, v0 row_ror:1 row_mask:0xf bank_mask:0xf bound_ctrl:1
	v_add_f32_dpp v54, v54, v54 row_ror:1 row_mask:0xf bank_mask:0xf bound_ctrl:1
	v_readlane_b32 s7, v0, 16
	v_readlane_b32 s9, v0, 48
	v_readlane_b32 s16, v54, 16
	v_readlane_b32 s17, v54, 48
	v_readlane_b32 s4, v0, 0
	v_readlane_b32 s5, v0, 32
	v_readlane_b32 s14, v54, 0
	v_readlane_b32 s15, v54, 32
	v_mov_b32_e32 v54, s7
	v_mov_b32_e32 v55, s9
	v_mov_b32_e32 v56, s16
	v_mov_b32_e32 v57, s17
	v_pk_add_f32 v[54:55], s[4:5], v[54:55]
	v_pk_add_f32 v[56:57], s[14:15], v[56:57]
	v_add_f32_e32 v0, v54, v55
	v_add_f32_e32 v54, v56, v57
	v_fmamk_f32 v0, v0, 0x3a800000, v213
	v_fmamk_f32 v54, v54, 0x3a800000, v213
	v_mul_f32_e32 v55, 0x4b800000, v0
	v_mul_f32_e32 v56, 0x4b800000, v54
	v_cmp_gt_f32_e32 vcc, s89, v54
	v_cmp_gt_f32_e64 s[4:5], s89, v0
	s_nop 0
	v_cndmask_b32_e32 v54, v54, v56, vcc
	v_cndmask_b32_e64 v0, v0, v55, s[4:5]
	v_rsq_f32_e32 v0, v0
	v_rsq_f32_e32 v54, v54
	v_mul_f32_e32 v55, 0x45800000, v0
	v_mul_f32_e32 v56, 0x45800000, v54
	v_cndmask_b32_e64 v0, v0, v55, s[4:5]
	v_cndmask_b32_e32 v54, v54, v56, vcc
	v_mul_f32_e32 v46, v46, v0
	v_mul_f32_e32 v47, v47, v0
	v_mul_f32_e32 v48, v48, v0
	v_mul_f32_e32 v49, v49, v0
	v_mul_f32_e32 v18, v18, v54
	v_mul_f32_e32 v19, v19, v54
	v_mul_f32_e32 v42, v42, v0
	v_mul_f32_e32 v43, v43, v0
	v_mul_f32_e32 v44, v44, v0
	v_mul_f32_e32 v45, v45, v0
	v_mul_f32_e32 v38, v38, v0
	v_mul_f32_e32 v39, v39, v0
	v_mul_f32_e32 v40, v40, v0
	v_mul_f32_e32 v41, v41, v0
	v_mul_f32_e32 v34, v34, v0
	v_mul_f32_e32 v35, v35, v0
	v_mul_f32_e32 v36, v36, v0
	v_mul_f32_e32 v0, v37, v0
	v_mul_f32_e32 v30, v30, v54
	v_mul_f32_e32 v31, v31, v54
	v_mul_f32_e32 v32, v32, v54
	v_mul_f32_e32 v33, v33, v54
	v_mul_f32_e32 v26, v26, v54
	v_mul_f32_e32 v27, v27, v54
	v_mul_f32_e32 v28, v28, v54
	v_mul_f32_e32 v29, v29, v54
	v_mul_f32_e32 v22, v22, v54
	v_mul_f32_e32 v23, v23, v54
	v_mul_f32_e32 v24, v24, v54
	v_mul_f32_e32 v25, v25, v54
	v_mul_f32_e32 v20, v20, v54
	v_mul_f32_e32 v21, v21, v54
	v_mul_f32_e32 v37, v10, v46
	v_mul_f32_e32 v46, v11, v47
	v_mul_f32_e32 v47, v12, v48
	v_mul_f32_e32 v48, v13, v49
	v_mul_f32_e32 v49, v14, v18
	v_mul_f32_e32 v54, v15, v19
	v_cvt_pk_bf16_f32 v18, v37, v46
	v_cvt_pk_bf16_f32 v19, v47, v48
	v_mul_f32_e32 v42, v2, v42
	v_mul_f32_e32 v43, v3, v43
	v_mul_f32_e32 v44, v4, v44
	v_mul_f32_e32 v45, v5, v45
	global_store_dwordx2 v[50:51], v[18:19], off offset:-2048
	v_cvt_pk_bf16_f32 v18, v42, v43
	v_cvt_pk_bf16_f32 v19, v44, v45
	v_mul_f32_e32 v38, v6, v38
	v_mul_f32_e32 v39, v7, v39
	v_mul_f32_e32 v40, v8, v40
	v_mul_f32_e32 v41, v9, v41
	global_store_dwordx2 v[50:51], v[18:19], off offset:-1536
	v_cvt_pk_bf16_f32 v18, v38, v39
	v_cvt_pk_bf16_f32 v19, v40, v41
	v_mul_f32_e32 v34, v14, v34
	v_mul_f32_e32 v35, v15, v35
	v_mul_f32_e32 v36, v16, v36
	v_mul_f32_e32 v0, v17, v0
	global_store_dwordx2 v[50:51], v[18:19], off offset:-1024
	v_cvt_pk_bf16_f32 v18, v34, v35
	v_cvt_pk_bf16_f32 v19, v36, v0
	v_mul_f32_e32 v30, v10, v30
	v_mul_f32_e32 v31, v11, v31
	v_mul_f32_e32 v32, v12, v32
	v_mul_f32_e32 v33, v13, v33
	global_store_dwordx2 v[50:51], v[18:19], off offset:-512
	v_cvt_pk_bf16_f32 v18, v30, v31
	v_cvt_pk_bf16_f32 v19, v32, v33
	v_mul_f32_e32 v26, v2, v26
	v_mul_f32_e32 v27, v3, v27
	v_mul_f32_e32 v28, v4, v28
	v_mul_f32_e32 v29, v5, v29
	global_store_dwordx2 v[50:51], v[18:19], off
	v_cvt_pk_bf16_f32 v18, v26, v27
	v_cvt_pk_bf16_f32 v19, v28, v29
	v_mul_f32_e32 v22, v6, v22
	v_mul_f32_e32 v23, v7, v23
	v_mul_f32_e32 v24, v8, v24
	v_mul_f32_e32 v25, v9, v25
	global_store_dwordx2 v[50:51], v[18:19], off offset:512
	v_cvt_pk_bf16_f32 v18, v22, v23
	v_cvt_pk_bf16_f32 v19, v24, v25
	v_mul_f32_e32 v20, v16, v20
	v_mul_f32_e32 v21, v17, v21
	global_store_dwordx2 v[50:51], v[18:19], off offset:1024
	v_cvt_pk_bf16_f32 v18, v49, v54
	v_cvt_pk_bf16_f32 v19, v20, v21
	global_store_dwordx2 v[50:51], v[18:19], off offset:1536
	v_lshl_add_u64 v[50:51], v[50:51], 0, s[10:11]
	s_add_i32 s8, s8, s6
	s_cmp_lt_i32 s8, 0x8000
	s_cbranch_scc0 .Lrms2_x_a
	s_add_i32 s28, s8, s6
	s_cmp_lt_i32 s28, 0x8000
	s_cbranch_scc0 .Lrms2_w0_ao
	s_cmp_lt_u32 s29, 2
	s_cbranch_scc1 .Lrms2_w0_ao
	s_waitcnt vmcnt(24)
	s_branch .Lrms2_go_ao

.Lrms2_go_ao:
	v_mov_b64_e32 v[18:19], v[164:165]
	v_mov_b64_e32 v[20:21], v[166:167]
	v_mov_b64_e32 v[22:23], v[168:169]
	v_mov_b64_e32 v[24:25], v[170:171]
	v_mov_b64_e32 v[26:27], v[172:173]
	v_mov_b64_e32 v[28:29], v[174:175]
	v_mov_b64_e32 v[30:31], v[176:177]
	v_mov_b64_e32 v[32:33], v[178:179]
	v_mov_b64_e32 v[34:35], v[180:181]
	v_mov_b64_e32 v[36:37], v[182:183]
	v_mov_b64_e32 v[38:39], v[184:185]
	v_mov_b64_e32 v[40:41], v[186:187]
	v_mov_b64_e32 v[42:43], v[188:189]
	v_mov_b64_e32 v[44:45], v[190:191]
	v_mov_b64_e32 v[46:47], v[192:193]
	v_mov_b64_e32 v[48:49], v[194:195]
	s_add_i32 s29, s29, 1
	s_add_i32 s28, s28, s6
	s_cmp_lt_i32 s28, 0x8000
	s_cbranch_scc0 .Lrms2_n_ao
	global_load_dwordx4 v[192:195], v[52:53], off offset:-4096
	global_load_dwordx4 v[188:191], v[52:53], off offset:-3072
	global_load_dwordx4 v[180:183], v[52:53], off offset:-1024
	global_load_dwordx4 v[184:187], v[52:53], off offset:-2048
	global_load_dwordx4 v[176:179], v[52:53], off
	global_load_dwordx4 v[172:175], v[52:53], off offset:1024
	global_load_dwordx4 v[164:167], v[52:53], off offset:3072
	global_load_dwordx4 v[168:171], v[52:53], off offset:2048
	v_lshl_add_u64 v[52:53], v[52:53], 0, s[12:13]
.Lrms2_n_ao:
	v_pk_mul_f32 v[54:55], v[48:49], v[48:49]
	v_pk_mul_f32 v[56:57], v[46:47], v[46:47]
	v_pk_mul_f32 v[58:59], v[44:45], v[44:45]
	v_pk_mul_f32 v[60:61], v[42:43], v[42:43]
	v_mul_f32_e32 v0, v39, v39
	v_mul_f32_e32 v62, v41, v41
	v_pk_mul_f32 v[64:65], v[32:33], v[32:33]
	v_pk_mul_f32 v[66:67], v[30:31], v[30:31]
	v_pk_mul_f32 v[68:69], v[28:29], v[28:29]
	v_pk_mul_f32 v[70:71], v[26:27], v[26:27]
	v_mul_f32_e32 v81, v36, v36
	v_mul_f32_e32 v82, v37, v37
	v_pk_mov_b32 v[76:77], v[56:57], v[54:55] op_sel:[1,0]
	v_mov_b32_e32 v57, v55
	v_pk_mov_b32 v[54:55], v[60:61], v[58:59] op_sel:[1,0]
	v_mov_b32_e32 v61, v59
	v_pk_fma_f32 v[58:59], v[38:39], v[38:39], v[0:1] op_sel_hi:[1,1,0]
	v_pk_fma_f32 v[62:63], v[40:41], v[40:41], v[62:63] op_sel_hi:[1,1,0]
	v_pk_mov_b32 v[78:79], v[66:67], v[64:65] op_sel:[1,0]
	v_mov_b32_e32 v67, v65
	v_pk_mov_b32 v[64:65], v[70:71], v[68:69] op_sel:[1,0]
	v_mov_b32_e32 v71, v69
	v_mul_f32_e32 v75, v34, v34
	v_mul_f32_e32 v72, v23, v23
	v_mul_f32_e32 v74, v25, v25
	v_pk_add_f32 v[56:57], v[76:77], v[56:57]
	v_pk_add_f32 v[54:55], v[54:55], v[60:61]
	v_mov_b32_e32 v59, v81
	v_mov_b32_e32 v63, v82
	v_pk_add_f32 v[60:61], v[78:79], v[66:67]
	v_pk_add_f32 v[64:65], v[64:65], v[70:71]
	v_mul_f32_e32 v80, v35, v35
	v_mul_f32_e32 v83, v18, v18
	v_mul_f32_e32 v84, v19, v19
	v_mul_f32_e32 v85, v20, v20
	v_mul_f32_e32 v86, v21, v21
	v_pk_fma_f32 v[68:69], v[22:23], v[22:23], v[72:73] op_sel_hi:[1,1,0]
	v_pk_fma_f32 v[72:73], v[24:25], v[24:25], v[74:75] op_sel_hi:[1,1,0]
	v_pk_add_f32 v[56:57], v[56:57], v[56:57] op_sel:[0,1] op_sel_hi:[1,0]
	v_pk_add_f32 v[54:55], v[54:55], v[54:55] op_sel:[0,1] op_sel_hi:[1,0]
	v_pk_add_f32 v[58:59], v[58:59], v[62:63]
	v_pk_add_f32 v[60:61], v[60:61], v[60:61] op_sel:[0,1] op_sel_hi:[1,0]
	v_pk_add_f32 v[62:63], v[64:65], v[64:65] op_sel:[0,1] op_sel_hi:[1,0]
	v_mov_b32_e32 v69, v85
	v_mov_b32_e32 v73, v86
	v_mov_b32_e32 v57, v75
	v_mov_b32_e32 v55, v80
	v_mov_b32_e32 v61, v83
	v_mov_b32_e32 v63, v84
	v_pk_add_f32 v[64:65], v[68:69], v[72:73]
	v_pk_add_f32 v[54:55], v[56:57], v[54:55]
	v_pk_add_f32 v[56:57], v[60:61], v[62:63]
	v_pk_add_f32 v[54:55], v[54:55], v[58:59]
	v_pk_add_f32 v[56:57], v[56:57], v[64:65]
	v_add_f32_e32 v0, v54, v55
	v_add_f32_e32 v54, v56, v57
	s_nop 0
	v_add_f32_dpp v0, v0, v0 row_ror:8 row_mask:0xf bank_mask:0xf bound_ctrl:1
	v_add_f32_dpp v54, v54, v54 row_ror:8 row_mask:0xf bank_mask:0xf bound_ctrl:1
	s_nop 0
	v_add_f32_dpp v0, v0, v0 row_ror:4 row_mask:0xf bank_mask:0xf bound_ctrl:1
	v_add_f32_dpp v54, v54, v54 row_ror:4 row_mask:0xf bank_mask:0xf bound_ctrl:1
	s_nop 0
	v_add_f32_dpp v0, v0, v0 row_ror:2 row_mask:0xf bank_mask:0xf bound_ctrl:1
	v_add_f32_dpp v54, v54, v54 row_ror:2 row_mask:0xf bank_mask:0xf bound_ctrl:1
	s_nop 0
	v_add_f32_dpp v0, v0, v0 row_ror:1 row_mask:0xf bank_mask:0xf bound_ctrl:1
	v_add_f32_dpp v54, v54, v54 row_ror:1 row_mask:0xf bank_mask:0xf bound_ctrl:1
	v_readlane_b32 s7, v0, 16
	v_readlane_b32 s9, v0, 48
	v_readlane_b32 s16, v54, 16
	v_readlane_b32 s17, v54, 48
	v_readlane_b32 s4, v0, 0
	v_readlane_b32 s5, v0, 32
	v_readlane_b32 s14, v54, 0
	v_readlane_b32 s15, v54, 32
	v_mov_b32_e32 v54, s7
	v_mov_b32_e32 v55, s9
	v_mov_b32_e32 v56, s16
	v_mov_b32_e32 v57, s17
	v_pk_add_f32 v[54:55], s[4:5], v[54:55]
	v_pk_add_f32 v[56:57], s[14:15], v[56:57]
	v_add_f32_e32 v0, v54, v55
	v_add_f32_e32 v54, v56, v57
	v_fmamk_f32 v0, v0, 0x3a800000, v213
	v_fmamk_f32 v54, v54, 0x3a800000, v213
	v_mul_f32_e32 v55, 0x4b800000, v0
	v_mul_f32_e32 v56, 0x4b800000, v54
	v_cmp_gt_f32_e32 vcc, s89, v54
	v_cmp_gt_f32_e64 s[4:5], s89, v0
	s_nop 0
	v_cndmask_b32_e32 v54, v54, v56, vcc
	v_cndmask_b32_e64 v0, v0, v55, s[4:5]
	v_rsq_f32_e32 v0, v0
	v_rsq_f32_e32 v54, v54
	v_mul_f32_e32 v55, 0x45800000, v0
	v_mul_f32_e32 v56, 0x45800000, v54
	v_cndmask_b32_e64 v0, v0, v55, s[4:5]
	v_cndmask_b32_e32 v54, v54, v56, vcc
	v_mul_f32_e32 v46, v46, v0
	v_mul_f32_e32 v47, v47, v0
	v_mul_f32_e32 v48, v48, v0
	v_mul_f32_e32 v49, v49, v0
	v_mul_f32_e32 v18, v18, v54
	v_mul_f32_e32 v19, v19, v54
	v_mul_f32_e32 v42, v42, v0
	v_mul_f32_e32 v43, v43, v0
	v_mul_f32_e32 v44, v44, v0
	v_mul_f32_e32 v45, v45, v0
	v_mul_f32_e32 v38, v38, v0
	v_mul_f32_e32 v39, v39, v0
	v_mul_f32_e32 v40, v40, v0
	v_mul_f32_e32 v41, v41, v0
	v_mul_f32_e32 v34, v34, v0
	v_mul_f32_e32 v35, v35, v0
	v_mul_f32_e32 v36, v36, v0
	v_mul_f32_e32 v0, v37, v0
	v_mul_f32_e32 v30, v30, v54
	v_mul_f32_e32 v31, v31, v54
	v_mul_f32_e32 v32, v32, v54
	v_mul_f32_e32 v33, v33, v54
	v_mul_f32_e32 v26, v26, v54
	v_mul_f32_e32 v27, v27, v54
	v_mul_f32_e32 v28, v28, v54
	v_mul_f32_e32 v29, v29, v54
	v_mul_f32_e32 v22, v22, v54
	v_mul_f32_e32 v23, v23, v54
	v_mul_f32_e32 v24, v24, v54
	v_mul_f32_e32 v25, v25, v54
	v_mul_f32_e32 v20, v20, v54
	v_mul_f32_e32 v21, v21, v54
	v_mul_f32_e32 v37, v10, v46
	v_mul_f32_e32 v46, v11, v47
	v_mul_f32_e32 v47, v12, v48
	v_mul_f32_e32 v48, v13, v49
	v_mul_f32_e32 v49, v14, v18
	v_mul_f32_e32 v54, v15, v19
	v_cvt_pk_bf16_f32 v18, v37, v46
	v_cvt_pk_bf16_f32 v19, v47, v48
	v_mul_f32_e32 v42, v2, v42
	v_mul_f32_e32 v43, v3, v43
	v_mul_f32_e32 v44, v4, v44
	v_mul_f32_e32 v45, v5, v45
	global_store_dwordx2 v[50:51], v[18:19], off offset:-2048
	v_cvt_pk_bf16_f32 v18, v42, v43
	v_cvt_pk_bf16_f32 v19, v44, v45
	v_mul_f32_e32 v38, v6, v38
	v_mul_f32_e32 v39, v7, v39
	v_mul_f32_e32 v40, v8, v40
	v_mul_f32_e32 v41, v9, v41
	global_store_dwordx2 v[50:51], v[18:19], off offset:-1536
	v_cvt_pk_bf16_f32 v18, v38, v39
	v_cvt_pk_bf16_f32 v19, v40, v41
	v_mul_f32_e32 v34, v14, v34
	v_mul_f32_e32 v35, v15, v35
	v_mul_f32_e32 v36, v16, v36
	v_mul_f32_e32 v0, v17, v0
	global_store_dwordx2 v[50:51], v[18:19], off offset:-1024
	v_cvt_pk_bf16_f32 v18, v34, v35
	v_cvt_pk_bf16_f32 v19, v36, v0
	v_mul_f32_e32 v30, v10, v30
	v_mul_f32_e32 v31, v11, v31
	v_mul_f32_e32 v32, v12, v32
	v_mul_f32_e32 v33, v13, v33
	global_store_dwordx2 v[50:51], v[18:19], off offset:-512
	v_cvt_pk_bf16_f32 v18, v30, v31
	v_cvt_pk_bf16_f32 v19, v32, v33
	v_mul_f32_e32 v26, v2, v26
	v_mul_f32_e32 v27, v3, v27
	v_mul_f32_e32 v28, v4, v28
	v_mul_f32_e32 v29, v5, v29
	global_store_dwordx2 v[50:51], v[18:19], off
	v_cvt_pk_bf16_f32 v18, v26, v27
	v_cvt_pk_bf16_f32 v19, v28, v29
	v_mul_f32_e32 v22, v6, v22
	v_mul_f32_e32 v23, v7, v23
	v_mul_f32_e32 v24, v8, v24
	v_mul_f32_e32 v25, v9, v25
	global_store_dwordx2 v[50:51], v[18:19], off offset:512
	v_cvt_pk_bf16_f32 v18, v22, v23
	v_cvt_pk_bf16_f32 v19, v24, v25
	v_mul_f32_e32 v20, v16, v20
	v_mul_f32_e32 v21, v17, v21
	global_store_dwordx2 v[50:51], v[18:19], off offset:1024
	v_cvt_pk_bf16_f32 v18, v49, v54
	v_cvt_pk_bf16_f32 v19, v20, v21
	global_store_dwordx2 v[50:51], v[18:19], off offset:1536
	v_lshl_add_u64 v[50:51], v[50:51], 0, s[10:11]
	s_add_i32 s8, s8, s6
	s_cmp_lt_i32 s8, 0x8000
	s_cbranch_scc1 .LBB0_131
.Lrms2_x_a:
.LBB0_132:
	s_mov_b64 s[6:7], 0
	s_getreg_b32 s8, hwreg(HW_REG_XCC_ID, 0, 4)
	s_waitcnt vmcnt(0)
	s_barrier
	s_and_saveexec_b64 s[4:5], s[84:85]
	s_cbranch_execz .LBB0_184
	v_readlane_b32 s9, v255, 21
	s_waitcnt vmcnt(0) expcnt(0) lgkmcnt(0)
	s_add_u32 s6, s94, s6
	v_mov_b32_e32 v0, s9
	ds_read_b32 v3, v0
	v_readlane_b32 s9, v255, 22
	s_addc_u32 s7, s95, s7
	s_and_b32 s52, s8, 15
	v_mov_b32_e32 v0, s9
	ds_read_b32 v0, v0
	s_waitcnt lgkmcnt(1)
	v_cmp_ne_u32_e32 vcc, 0, v3
	s_cbranch_vccnz .LBB0_148
	s_add_u32 s8, s6, 0x2f00200
	s_addc_u32 s9, s7, 0
	s_add_u32 s10, s6, 0x2f00400
	s_addc_u32 s11, s7, 0
	s_add_u32 s12, s6, 0x2f00500
	s_addc_u32 s13, s7, 0
	s_add_u32 s14, s6, 0x2f00600
	s_addc_u32 s15, s7, 0
	s_add_u32 s16, s6, 0x2f00700
	s_addc_u32 s17, s7, 0
	s_add_u32 s18, s6, 0x2f00800
	s_addc_u32 s19, s7, 0
	s_add_u32 s20, s6, 0x2f00900
	s_addc_u32 s21, s7, 0
	s_add_u32 s22, s6, 0x2f00a00
	s_addc_u32 s23, s7, 0
	s_add_u32 s24, s6, 0x2f00b00
	s_addc_u32 s25, s7, 0
	s_add_u32 s26, s6, 0x2f00c00
	s_addc_u32 s27, s7, 0
	s_add_u32 s28, s6, 0x2f00d00
	s_addc_u32 s29, s7, 0
	s_add_u32 s30, s6, 0x2f00e00
	s_addc_u32 s31, s7, 0
	s_add_u32 s34, s6, 0x2f00f00
	s_addc_u32 s35, s7, 0
	s_add_u32 s36, s6, 0x2f01000
	s_addc_u32 s37, s7, 0
	s_add_u32 s38, s6, 0x2f01100
	s_addc_u32 s39, s7, 0
	s_add_u32 s40, s6, 0x2f01200
	s_addc_u32 s41, s7, 0
	s_add_u32 s42, s6, 0x2f01300
	s_addc_u32 s43, s7, 0
	s_mov_b32 s53, 1
	s_branch .LBB0_136

.LBB0_336:
	v_mov_b32_e32 v0, v212
	v_readlane_b32 s6, v254, 9
	v_readfirstlane_b32 s4, v0
	s_ashr_i32 s5, s4, 6
	s_mov_b32 s4, s6
	v_readlane_b32 s6, v254, 0
	s_lshl_b32 s6, s6, 3
	s_add_i32 s5, s6, s5
	s_mov_b64 s[8:9], 0
	s_cmpk_gt_i32 s5, 0x3fff
	v_readlane_b32 s7, v254, 10
	s_cbranch_scc1 .LBB0_339
	v_readlane_b32 s12, v254, 13
	s_mul_i32 s6, s68, 0x3000
	v_readlane_b32 s16, v254, 17
	v_and_b32_e32 v18, 63, v0
	s_mul_hi_i32 s7, s68, 0x3000
	v_readlane_b32 s17, v254, 18
	s_add_u32 s6, s16, s6
	s_addc_u32 s7, s17, s7
	v_lshlrev_b32_e32 v0, 4, v18
	v_lshl_add_u64 v[2:3], s[6:7], 0, v[0:1]
	s_mov_b64 s[6:7], 0x1000
	v_add_co_u32_e32 v10, vcc, 0x1000, v2
	v_lshl_add_u64 v[14:15], v[2:3], 0, s[6:7]
	s_nop 0
	v_addc_co_u32_e32 v11, vcc, 0, v3, vcc
	global_load_dwordx4 v[2:5], v[14:15], off offset:1024
	global_load_dwordx4 v[6:9], v[14:15], off offset:2048
	s_nop 0
	global_load_dwordx4 v[10:13], v[10:11], off
	s_nop 0
	global_load_dwordx4 v[14:17], v[14:15], off offset:3072
	s_lshl_b32 s6, s5, 1
	s_ashr_i32 s7, s6, 31
	s_lshl_b32 s4, s4, 4
	s_lshl_b64 s[10:11], s[6:7], 11
	s_add_u32 s5, s8, s10
	s_addc_u32 s9, s9, s11
	v_readlane_b32 s8, v255, 11
	s_add_u32 s8, s8, s5
	v_readlane_b32 s5, v255, 12
	v_lshlrev_b32_e32 v18, 3, v18
	v_mov_b32_e32 v19, v1
	s_addc_u32 s9, s5, s9
	s_ashr_i32 s5, s4, 31
	v_lshl_add_u64 v[18:19], s[8:9], 0, v[18:19]
	s_lshl_b64 s[8:9], s[4:5], 11
	s_lshl_b64 s[10:11], s[6:7], 12
	v_readlane_b32 s7, v255, 13
	s_add_u32 s10, s7, s10
	v_readlane_b32 s7, v255, 14
	s_addc_u32 s11, s7, s11
	v_lshl_add_u64 v[20:21], s[10:11], 0, v[0:1]
	s_lshl_b64 s[10:11], s[4:5], 12
	v_readlane_b32 s13, v254, 14
	v_readlane_b32 s14, v254, 15
	v_readlane_b32 s15, v254, 16
	v_readlane_b32 s18, v254, 19
	v_readlane_b32 s19, v254, 20
	v_readlane_b32 s20, v254, 21
	v_readlane_b32 s21, v254, 22
	v_readlane_b32 s22, v254, 23
	v_readlane_b32 s23, v254, 24
	v_readlane_b32 s24, v254, 25
	v_readlane_b32 s25, v254, 26
	v_readlane_b32 s26, v254, 27
	v_readlane_b32 s27, v254, 28
	global_load_dwordx4 v[88:91], v[20:21], off offset:-4096
	global_load_dwordx4 v[92:95], v[20:21], off offset:-3072
	global_load_dwordx4 v[96:99], v[20:21], off offset:-2048
	global_load_dwordx4 v[100:103], v[20:21], off offset:-1024
	global_load_dwordx4 v[104:107], v[20:21], off
	global_load_dwordx4 v[108:111], v[20:21], off offset:1024
	global_load_dwordx4 v[112:115], v[20:21], off offset:2048
	global_load_dwordx4 v[116:119], v[20:21], off offset:3072
	v_lshl_add_u64 v[20:21], v[20:21], 0, s[10:11]
	s_mov_b32 s29, 0
	s_add_i32 s28, s6, s4
	s_cmp_lt_i32 s28, 0x8000
	s_cbranch_scc0 .Lrms2_p_b
	global_load_dwordx4 v[164:167], v[20:21], off offset:-4096
	global_load_dwordx4 v[168:171], v[20:21], off offset:-3072
	global_load_dwordx4 v[172:175], v[20:21], off offset:-2048
	global_load_dwordx4 v[176:179], v[20:21], off offset:-1024
	global_load_dwordx4 v[180:183], v[20:21], off
	global_load_dwordx4 v[184:187], v[20:21], off offset:1024
	global_load_dwordx4 v[188:191], v[20:21], off offset:2048
	global_load_dwordx4 v[192:195], v[20:21], off offset:3072
	v_lshl_add_u64 v[20:21], v[20:21], 0, s[10:11]
.Lrms2_p_b:
.LBB0_338:
	s_add_i32 s28, s6, s4
	s_cmp_lt_i32 s28, 0x8000
	s_cbranch_scc0 .Lrms2_w0_be
	s_cmp_lt_u32 s29, 2
	s_cbranch_scc1 .Lrms2_w0_be
	s_waitcnt vmcnt(24)
	s_branch .Lrms2_go_be

.Lrms2_go_be:
	v_mov_b64_e32 v[22:23], v[88:89]
	v_mov_b64_e32 v[24:25], v[90:91]
	v_mov_b64_e32 v[26:27], v[92:93]
	v_mov_b64_e32 v[28:29], v[94:95]
	v_mov_b64_e32 v[30:31], v[96:97]
	v_mov_b64_e32 v[32:33], v[98:99]
	v_mov_b64_e32 v[34:35], v[100:101]
	v_mov_b64_e32 v[36:37], v[102:103]
	v_mov_b64_e32 v[38:39], v[104:105]
	v_mov_b64_e32 v[40:41], v[106:107]
	v_mov_b64_e32 v[42:43], v[108:109]
	v_mov_b64_e32 v[44:45], v[110:111]
	v_mov_b64_e32 v[46:47], v[112:113]
	v_mov_b64_e32 v[48:49], v[114:115]
	v_mov_b64_e32 v[50:51], v[116:117]
	v_mov_b64_e32 v[52:53], v[118:119]
	s_add_i32 s29, s29, 1
	s_add_i32 s28, s28, s4
	s_cmp_lt_i32 s28, 0x8000
	s_cbranch_scc0 .Lrms2_n_be
	global_load_dwordx4 v[88:91], v[20:21], off offset:-4096
	global_load_dwordx4 v[92:95], v[20:21], off offset:-3072
	global_load_dwordx4 v[96:99], v[20:21], off offset:-2048
	global_load_dwordx4 v[100:103], v[20:21], off offset:-1024
	global_load_dwordx4 v[104:107], v[20:21], off
	global_load_dwordx4 v[108:111], v[20:21], off offset:1024
	global_load_dwordx4 v[112:115], v[20:21], off offset:2048
	global_load_dwordx4 v[116:119], v[20:21], off offset:3072
	v_lshl_add_u64 v[20:21], v[20:21], 0, s[10:11]
.Lrms2_n_be:
	v_pk_mul_f32 v[54:55], v[24:25], v[24:25]
	v_pk_mul_f32 v[56:57], v[22:23], v[22:23]
	v_mul_f32_e32 v0, v34, v34
	v_pk_mov_b32 v[58:59], v[56:57], v[54:55] op_sel:[1,0]
	v_mov_b32_e32 v57, v55
	v_pk_add_f32 v[54:55], v[58:59], v[56:57]
	v_pk_mul_f32 v[56:57], v[28:29], v[28:29]
	v_pk_mul_f32 v[58:59], v[26:27], v[26:27]
	v_pk_add_f32 v[54:55], v[54:55], v[54:55] op_sel:[0,1] op_sel_hi:[1,0]
	v_pk_mov_b32 v[60:61], v[58:59], v[56:57] op_sel:[1,0]
	v_mov_b32_e32 v59, v57
	v_pk_add_f32 v[56:57], v[60:61], v[58:59]
	v_mul_f32_e32 v58, v35, v35
	v_pk_add_f32 v[56:57], v[56:57], v[56:57] op_sel:[0,1] op_sel_hi:[1,0]
	v_mov_b32_e32 v55, v0
	v_mov_b32_e32 v57, v58
	v_mul_f32_e32 v0, v31, v31
	v_mul_f32_e32 v59, v36, v36
	v_pk_add_f32 v[54:55], v[54:55], v[56:57]
	v_pk_fma_f32 v[56:57], v[30:31], v[30:31], v[0:1] op_sel_hi:[1,1,0]
	v_mul_f32_e32 v0, v33, v33
	v_mul_f32_e32 v60, v37, v37
	v_mov_b32_e32 v57, v59
	v_pk_fma_f32 v[58:59], v[32:33], v[32:33], v[0:1] op_sel_hi:[1,1,0]
	v_mul_f32_e32 v0, v50, v50
	v_mov_b32_e32 v59, v60
	v_pk_add_f32 v[56:57], v[56:57], v[58:59]
	s_nop 0
	v_pk_add_f32 v[54:55], v[54:55], v[56:57]
	v_pk_mul_f32 v[56:57], v[38:39], v[38:39]
	v_add_f32_e32 v62, v54, v55
	v_pk_mul_f32 v[54:55], v[40:41], v[40:41]
	s_nop 0
	v_pk_mov_b32 v[58:59], v[56:57], v[54:55] op_sel:[1,0]
	v_mov_b32_e32 v57, v55
	v_pk_add_f32 v[54:55], v[58:59], v[56:57]
	v_pk_mul_f32 v[56:57], v[44:45], v[44:45]
	v_pk_mul_f32 v[58:59], v[42:43], v[42:43]
	v_pk_add_f32 v[54:55], v[54:55], v[54:55] op_sel:[0,1] op_sel_hi:[1,0]
	v_pk_mov_b32 v[60:61], v[58:59], v[56:57] op_sel:[1,0]
	v_mov_b32_e32 v59, v57
	v_pk_add_f32 v[56:57], v[60:61], v[58:59]
	v_mul_f32_e32 v58, v51, v51
	v_pk_add_f32 v[56:57], v[56:57], v[56:57] op_sel:[0,1] op_sel_hi:[1,0]
	v_mov_b32_e32 v55, v0
	v_mov_b32_e32 v57, v58
	v_mul_f32_e32 v0, v47, v47
	v_mul_f32_e32 v59, v52, v52
	v_pk_add_f32 v[54:55], v[54:55], v[56:57]
	v_pk_fma_f32 v[56:57], v[46:47], v[46:47], v[0:1] op_sel_hi:[1,1,0]
	v_mul_f32_e32 v0, v49, v49
	v_mul_f32_e32 v60, v53, v53
	v_mov_b32_e32 v57, v59
	v_pk_fma_f32 v[58:59], v[48:49], v[48:49], v[0:1] op_sel_hi:[1,1,0]
	s_nop 0
	v_mov_b32_e32 v59, v60
	v_pk_add_f32 v[56:57], v[56:57], v[58:59]
	s_nop 0
	v_pk_add_f32 v[54:55], v[54:55], v[56:57]
	s_nop 0
	v_add_f32_e32 v0, v54, v55
	v_add_f32_dpp v54, v62, v62 row_ror:8 row_mask:0xf bank_mask:0xf bound_ctrl:1
	s_nop 0
	v_add_f32_dpp v0, v0, v0 row_ror:8 row_mask:0xf bank_mask:0xf bound_ctrl:1
	v_add_f32_dpp v54, v54, v54 row_ror:4 row_mask:0xf bank_mask:0xf bound_ctrl:1
	s_nop 0
	v_add_f32_dpp v0, v0, v0 row_ror:4 row_mask:0xf bank_mask:0xf bound_ctrl:1
	v_add_f32_dpp v54, v54, v54 row_ror:2 row_mask:0xf bank_mask:0xf bound_ctrl:1
	s_nop 0
	v_add_f32_dpp v0, v0, v0 row_ror:2 row_mask:0xf bank_mask:0xf bound_ctrl:1
	v_add_f32_dpp v54, v54, v54 row_ror:1 row_mask:0xf bank_mask:0xf bound_ctrl:1
	s_nop 0
	v_readlane_b32 s5, v54, 16
	v_readlane_b32 s7, v54, 48
	v_readlane_b32 s12, v54, 0
	v_readlane_b32 s13, v54, 32
	v_mov_b32_e32 v54, s5
	v_mov_b32_e32 v55, s7
	v_pk_add_f32 v[54:55], s[12:13], v[54:55]
	v_add_f32_dpp v0, v0, v0 row_ror:1 row_mask:0xf bank_mask:0xf bound_ctrl:1
	v_add_f32_e32 v54, v54, v55
	v_fmamk_f32 v54, v54, 0x3a800000, v213
	v_cmp_gt_f32_e32 vcc, s89, v54
	v_mul_f32_e32 v55, 0x4b800000, v54
	v_readlane_b32 s5, v0, 16
	v_cndmask_b32_e32 v54, v54, v55, vcc
	v_rsq_f32_e32 v54, v54
	v_readlane_b32 s7, v0, 48
	v_readlane_b32 s12, v0, 0
	v_readlane_b32 s13, v0, 32
	v_mul_f32_e32 v55, 0x45800000, v54
	v_cndmask_b32_e32 v54, v54, v55, vcc
	v_mul_f32_e32 v22, v22, v54
	v_mul_f32_e32 v23, v23, v54
	v_mul_f32_e32 v22, v10, v22
	v_mul_f32_e32 v23, v11, v23
	v_cvt_pk_bf16_f32 v22, v22, v23
	v_mul_f32_e32 v23, v24, v54
	v_mul_f32_e32 v23, v12, v23
	v_mul_f32_e32 v24, v25, v54
	v_mul_f32_e32 v24, v13, v24
	v_cvt_pk_bf16_f32 v23, v23, v24
	global_store_dwordx2 v[18:19], v[22:23], off offset:-2048
	v_mul_f32_e32 v22, v26, v54
	v_mul_f32_e32 v23, v27, v54
	v_mul_f32_e32 v22, v2, v22
	v_mul_f32_e32 v23, v3, v23
	v_cvt_pk_bf16_f32 v22, v22, v23
	v_mul_f32_e32 v23, v28, v54
	v_mul_f32_e32 v23, v4, v23
	v_mul_f32_e32 v24, v29, v54
	v_mul_f32_e32 v24, v5, v24
	v_cvt_pk_bf16_f32 v23, v23, v24
	global_store_dwordx2 v[18:19], v[22:23], off offset:-1536
	v_mul_f32_e32 v22, v30, v54
	v_mul_f32_e32 v23, v31, v54
	v_mul_f32_e32 v22, v6, v22
	v_mul_f32_e32 v23, v7, v23
	v_cvt_pk_bf16_f32 v22, v22, v23
	v_mul_f32_e32 v23, v32, v54
	v_mul_f32_e32 v23, v8, v23
	v_mul_f32_e32 v24, v33, v54
	v_mul_f32_e32 v24, v9, v24
	v_cvt_pk_bf16_f32 v23, v23, v24
	global_store_dwordx2 v[18:19], v[22:23], off offset:-1024
	v_mul_f32_e32 v22, v34, v54
	v_mul_f32_e32 v23, v35, v54
	v_mul_f32_e32 v22, v14, v22
	v_mul_f32_e32 v23, v15, v23
	v_cvt_pk_bf16_f32 v22, v22, v23
	v_mul_f32_e32 v23, v36, v54
	v_mul_f32_e32 v23, v16, v23
	v_mul_f32_e32 v24, v37, v54
	v_mul_f32_e32 v24, v17, v24
	v_cvt_pk_bf16_f32 v23, v23, v24
	global_store_dwordx2 v[18:19], v[22:23], off offset:-512
	v_mov_b32_e32 v22, s5
	v_mov_b32_e32 v23, s7
	v_pk_add_f32 v[22:23], s[12:13], v[22:23]
	s_nop 0
	v_add_f32_e32 v0, v22, v23
	v_fmamk_f32 v0, v0, 0x3a800000, v213
	v_cmp_gt_f32_e32 vcc, s89, v0
	v_mul_f32_e32 v22, 0x4b800000, v0
	s_nop 0
	v_cndmask_b32_e32 v0, v0, v22, vcc
	v_rsq_f32_e32 v0, v0
	s_nop 0
	v_mul_f32_e32 v22, 0x45800000, v0
	v_cndmask_b32_e32 v0, v0, v22, vcc
	v_mul_f32_e32 v22, v38, v0
	v_mul_f32_e32 v23, v39, v0
	v_mul_f32_e32 v22, v10, v22
	v_mul_f32_e32 v23, v11, v23
	v_cvt_pk_bf16_f32 v22, v22, v23
	v_mul_f32_e32 v23, v40, v0
	v_mul_f32_e32 v23, v12, v23
	v_mul_f32_e32 v24, v41, v0
	v_mul_f32_e32 v24, v13, v24
	v_cvt_pk_bf16_f32 v23, v23, v24
	global_store_dwordx2 v[18:19], v[22:23], off
	v_mul_f32_e32 v22, v42, v0
	v_mul_f32_e32 v23, v43, v0
	v_mul_f32_e32 v22, v2, v22
	v_mul_f32_e32 v23, v3, v23
	v_cvt_pk_bf16_f32 v22, v22, v23
	v_mul_f32_e32 v23, v44, v0
	v_mul_f32_e32 v23, v4, v23
	v_mul_f32_e32 v24, v45, v0
	v_mul_f32_e32 v24, v5, v24
	v_cvt_pk_bf16_f32 v23, v23, v24
	global_store_dwordx2 v[18:19], v[22:23], off offset:512
	v_mul_f32_e32 v22, v46, v0
	v_mul_f32_e32 v23, v47, v0
	v_mul_f32_e32 v22, v6, v22
	v_mul_f32_e32 v23, v7, v23
	v_cvt_pk_bf16_f32 v22, v22, v23
	v_mul_f32_e32 v23, v48, v0
	v_mul_f32_e32 v23, v8, v23
	v_mul_f32_e32 v24, v49, v0
	v_mul_f32_e32 v24, v9, v24
	v_cvt_pk_bf16_f32 v23, v23, v24
	global_store_dwordx2 v[18:19], v[22:23], off offset:1024
	v_mul_f32_e32 v22, v50, v0
	v_mul_f32_e32 v23, v51, v0
	v_mul_f32_e32 v22, v14, v22
	v_mul_f32_e32 v23, v15, v23
	v_cvt_pk_bf16_f32 v22, v22, v23
	v_mul_f32_e32 v23, v52, v0
	v_mul_f32_e32 v23, v16, v23
	v_mul_f32_e32 v0, v53, v0
	v_mul_f32_e32 v0, v17, v0
	v_cvt_pk_bf16_f32 v23, v23, v0
	global_store_dwordx2 v[18:19], v[22:23], off offset:1536
	v_lshl_add_u64 v[18:19], v[18:19], 0, s[8:9]
	s_add_i32 s6, s6, s4
	s_cmp_lt_i32 s6, 0x8000
	s_cbranch_scc0 .Lrms2_x_b
	s_add_i32 s28, s6, s4
	s_cmp_lt_i32 s28, 0x8000
	s_cbranch_scc0 .Lrms2_w0_bo
	s_cmp_lt_u32 s29, 2
	s_cbranch_scc1 .Lrms2_w0_bo
	s_waitcnt vmcnt(24)
	s_branch .Lrms2_go_bo

.Lrms2_go_bo:
	v_mov_b64_e32 v[22:23], v[164:165]
	v_mov_b64_e32 v[24:25], v[166:167]
	v_mov_b64_e32 v[26:27], v[168:169]
	v_mov_b64_e32 v[28:29], v[170:171]
	v_mov_b64_e32 v[30:31], v[172:173]
	v_mov_b64_e32 v[32:33], v[174:175]
	v_mov_b64_e32 v[34:35], v[176:177]
	v_mov_b64_e32 v[36:37], v[178:179]
	v_mov_b64_e32 v[38:39], v[180:181]
	v_mov_b64_e32 v[40:41], v[182:183]
	v_mov_b64_e32 v[42:43], v[184:185]
	v_mov_b64_e32 v[44:45], v[186:187]
	v_mov_b64_e32 v[46:47], v[188:189]
	v_mov_b64_e32 v[48:49], v[190:191]
	v_mov_b64_e32 v[50:51], v[192:193]
	v_mov_b64_e32 v[52:53], v[194:195]
	s_add_i32 s29, s29, 1
	s_add_i32 s28, s28, s4
	s_cmp_lt_i32 s28, 0x8000
	s_cbranch_scc0 .Lrms2_n_bo
	global_load_dwordx4 v[164:167], v[20:21], off offset:-4096
	global_load_dwordx4 v[168:171], v[20:21], off offset:-3072
	global_load_dwordx4 v[172:175], v[20:21], off offset:-2048
	global_load_dwordx4 v[176:179], v[20:21], off offset:-1024
	global_load_dwordx4 v[180:183], v[20:21], off
	global_load_dwordx4 v[184:187], v[20:21], off offset:1024
	global_load_dwordx4 v[188:191], v[20:21], off offset:2048
	global_load_dwordx4 v[192:195], v[20:21], off offset:3072
	v_lshl_add_u64 v[20:21], v[20:21], 0, s[10:11]
.Lrms2_n_bo:
	v_pk_mul_f32 v[54:55], v[24:25], v[24:25]
	v_pk_mul_f32 v[56:57], v[22:23], v[22:23]
	v_mul_f32_e32 v0, v34, v34
	v_pk_mov_b32 v[58:59], v[56:57], v[54:55] op_sel:[1,0]
	v_mov_b32_e32 v57, v55
	v_pk_add_f32 v[54:55], v[58:59], v[56:57]
	v_pk_mul_f32 v[56:57], v[28:29], v[28:29]
	v_pk_mul_f32 v[58:59], v[26:27], v[26:27]
	v_pk_add_f32 v[54:55], v[54:55], v[54:55] op_sel:[0,1] op_sel_hi:[1,0]
	v_pk_mov_b32 v[60:61], v[58:59], v[56:57] op_sel:[1,0]
	v_mov_b32_e32 v59, v57
	v_pk_add_f32 v[56:57], v[60:61], v[58:59]
	v_mul_f32_e32 v58, v35, v35
	v_pk_add_f32 v[56:57], v[56:57], v[56:57] op_sel:[0,1] op_sel_hi:[1,0]
	v_mov_b32_e32 v55, v0
	v_mov_b32_e32 v57, v58
	v_mul_f32_e32 v0, v31, v31
	v_mul_f32_e32 v59, v36, v36
	v_pk_add_f32 v[54:55], v[54:55], v[56:57]
	v_pk_fma_f32 v[56:57], v[30:31], v[30:31], v[0:1] op_sel_hi:[1,1,0]
	v_mul_f32_e32 v0, v33, v33
	v_mul_f32_e32 v60, v37, v37
	v_mov_b32_e32 v57, v59
	v_pk_fma_f32 v[58:59], v[32:33], v[32:33], v[0:1] op_sel_hi:[1,1,0]
	v_mul_f32_e32 v0, v50, v50
	v_mov_b32_e32 v59, v60
	v_pk_add_f32 v[56:57], v[56:57], v[58:59]
	s_nop 0
	v_pk_add_f32 v[54:55], v[54:55], v[56:57]
	v_pk_mul_f32 v[56:57], v[38:39], v[38:39]
	v_add_f32_e32 v62, v54, v55
	v_pk_mul_f32 v[54:55], v[40:41], v[40:41]
	s_nop 0
	v_pk_mov_b32 v[58:59], v[56:57], v[54:55] op_sel:[1,0]
	v_mov_b32_e32 v57, v55
	v_pk_add_f32 v[54:55], v[58:59], v[56:57]
	v_pk_mul_f32 v[56:57], v[44:45], v[44:45]
	v_pk_mul_f32 v[58:59], v[42:43], v[42:43]
	v_pk_add_f32 v[54:55], v[54:55], v[54:55] op_sel:[0,1] op_sel_hi:[1,0]
	v_pk_mov_b32 v[60:61], v[58:59], v[56:57] op_sel:[1,0]
	v_mov_b32_e32 v59, v57
	v_pk_add_f32 v[56:57], v[60:61], v[58:59]
	v_mul_f32_e32 v58, v51, v51
	v_pk_add_f32 v[56:57], v[56:57], v[56:57] op_sel:[0,1] op_sel_hi:[1,0]
	v_mov_b32_e32 v55, v0
	v_mov_b32_e32 v57, v58
	v_mul_f32_e32 v0, v47, v47
	v_mul_f32_e32 v59, v52, v52
	v_pk_add_f32 v[54:55], v[54:55], v[56:57]
	v_pk_fma_f32 v[56:57], v[46:47], v[46:47], v[0:1] op_sel_hi:[1,1,0]
	v_mul_f32_e32 v0, v49, v49
	v_mul_f32_e32 v60, v53, v53
	v_mov_b32_e32 v57, v59
	v_pk_fma_f32 v[58:59], v[48:49], v[48:49], v[0:1] op_sel_hi:[1,1,0]
	s_nop 0
	v_mov_b32_e32 v59, v60
	v_pk_add_f32 v[56:57], v[56:57], v[58:59]
	s_nop 0
	v_pk_add_f32 v[54:55], v[54:55], v[56:57]
	s_nop 0
	v_add_f32_e32 v0, v54, v55
	v_add_f32_dpp v54, v62, v62 row_ror:8 row_mask:0xf bank_mask:0xf bound_ctrl:1
	s_nop 0
	v_add_f32_dpp v0, v0, v0 row_ror:8 row_mask:0xf bank_mask:0xf bound_ctrl:1
	v_add_f32_dpp v54, v54, v54 row_ror:4 row_mask:0xf bank_mask:0xf bound_ctrl:1
	s_nop 0
	v_add_f32_dpp v0, v0, v0 row_ror:4 row_mask:0xf bank_mask:0xf bound_ctrl:1
	v_add_f32_dpp v54, v54, v54 row_ror:2 row_mask:0xf bank_mask:0xf bound_ctrl:1
	s_nop 0
	v_add_f32_dpp v0, v0, v0 row_ror:2 row_mask:0xf bank_mask:0xf bound_ctrl:1
	v_add_f32_dpp v54, v54, v54 row_ror:1 row_mask:0xf bank_mask:0xf bound_ctrl:1
	s_nop 0
	v_readlane_b32 s5, v54, 16
	v_readlane_b32 s7, v54, 48
	v_readlane_b32 s12, v54, 0
	v_readlane_b32 s13, v54, 32
	v_mov_b32_e32 v54, s5
	v_mov_b32_e32 v55, s7
	v_pk_add_f32 v[54:55], s[12:13], v[54:55]
	v_add_f32_dpp v0, v0, v0 row_ror:1 row_mask:0xf bank_mask:0xf bound_ctrl:1
	v_add_f32_e32 v54, v54, v55
	v_fmamk_f32 v54, v54, 0x3a800000, v213
	v_cmp_gt_f32_e32 vcc, s89, v54
	v_mul_f32_e32 v55, 0x4b800000, v54
	v_readlane_b32 s5, v0, 16
	v_cndmask_b32_e32 v54, v54, v55, vcc
	v_rsq_f32_e32 v54, v54
	v_readlane_b32 s7, v0, 48
	v_readlane_b32 s12, v0, 0
	v_readlane_b32 s13, v0, 32
	v_mul_f32_e32 v55, 0x45800000, v54
	v_cndmask_b32_e32 v54, v54, v55, vcc
	v_mul_f32_e32 v22, v22, v54
	v_mul_f32_e32 v23, v23, v54
	v_mul_f32_e32 v22, v10, v22
	v_mul_f32_e32 v23, v11, v23
	v_cvt_pk_bf16_f32 v22, v22, v23
	v_mul_f32_e32 v23, v24, v54
	v_mul_f32_e32 v23, v12, v23
	v_mul_f32_e32 v24, v25, v54
	v_mul_f32_e32 v24, v13, v24
	v_cvt_pk_bf16_f32 v23, v23, v24
	global_store_dwordx2 v[18:19], v[22:23], off offset:-2048
	v_mul_f32_e32 v22, v26, v54
	v_mul_f32_e32 v23, v27, v54
	v_mul_f32_e32 v22, v2, v22
	v_mul_f32_e32 v23, v3, v23
	v_cvt_pk_bf16_f32 v22, v22, v23
	v_mul_f32_e32 v23, v28, v54
	v_mul_f32_e32 v23, v4, v23
	v_mul_f32_e32 v24, v29, v54
	v_mul_f32_e32 v24, v5, v24
	v_cvt_pk_bf16_f32 v23, v23, v24
	global_store_dwordx2 v[18:19], v[22:23], off offset:-1536
	v_mul_f32_e32 v22, v30, v54
	v_mul_f32_e32 v23, v31, v54
	v_mul_f32_e32 v22, v6, v22
	v_mul_f32_e32 v23, v7, v23
	v_cvt_pk_bf16_f32 v22, v22, v23
	v_mul_f32_e32 v23, v32, v54
	v_mul_f32_e32 v23, v8, v23
	v_mul_f32_e32 v24, v33, v54
	v_mul_f32_e32 v24, v9, v24
	v_cvt_pk_bf16_f32 v23, v23, v24
	global_store_dwordx2 v[18:19], v[22:23], off offset:-1024
	v_mul_f32_e32 v22, v34, v54
	v_mul_f32_e32 v23, v35, v54
	v_mul_f32_e32 v22, v14, v22
	v_mul_f32_e32 v23, v15, v23
	v_cvt_pk_bf16_f32 v22, v22, v23
	v_mul_f32_e32 v23, v36, v54
	v_mul_f32_e32 v23, v16, v23
	v_mul_f32_e32 v24, v37, v54
	v_mul_f32_e32 v24, v17, v24
	v_cvt_pk_bf16_f32 v23, v23, v24
	global_store_dwordx2 v[18:19], v[22:23], off offset:-512
	v_mov_b32_e32 v22, s5
	v_mov_b32_e32 v23, s7
	v_pk_add_f32 v[22:23], s[12:13], v[22:23]
	s_nop 0
	v_add_f32_e32 v0, v22, v23
	v_fmamk_f32 v0, v0, 0x3a800000, v213
	v_cmp_gt_f32_e32 vcc, s89, v0
	v_mul_f32_e32 v22, 0x4b800000, v0
	s_nop 0
	v_cndmask_b32_e32 v0, v0, v22, vcc
	v_rsq_f32_e32 v0, v0
	s_nop 0
	v_mul_f32_e32 v22, 0x45800000, v0
	v_cndmask_b32_e32 v0, v0, v22, vcc
	v_mul_f32_e32 v22, v38, v0
	v_mul_f32_e32 v23, v39, v0
	v_mul_f32_e32 v22, v10, v22
	v_mul_f32_e32 v23, v11, v23
	v_cvt_pk_bf16_f32 v22, v22, v23
	v_mul_f32_e32 v23, v40, v0
	v_mul_f32_e32 v23, v12, v23
	v_mul_f32_e32 v24, v41, v0
	v_mul_f32_e32 v24, v13, v24
	v_cvt_pk_bf16_f32 v23, v23, v24
	global_store_dwordx2 v[18:19], v[22:23], off
	v_mul_f32_e32 v22, v42, v0
	v_mul_f32_e32 v23, v43, v0
	v_mul_f32_e32 v22, v2, v22
	v_mul_f32_e32 v23, v3, v23
	v_cvt_pk_bf16_f32 v22, v22, v23
	v_mul_f32_e32 v23, v44, v0
	v_mul_f32_e32 v23, v4, v23
	v_mul_f32_e32 v24, v45, v0
	v_mul_f32_e32 v24, v5, v24
	v_cvt_pk_bf16_f32 v23, v23, v24
	global_store_dwordx2 v[18:19], v[22:23], off offset:512
	v_mul_f32_e32 v22, v46, v0
	v_mul_f32_e32 v23, v47, v0
	v_mul_f32_e32 v22, v6, v22
	v_mul_f32_e32 v23, v7, v23
	v_cvt_pk_bf16_f32 v22, v22, v23
	v_mul_f32_e32 v23, v48, v0
	v_mul_f32_e32 v23, v8, v23
	v_mul_f32_e32 v24, v49, v0
	v_mul_f32_e32 v24, v9, v24
	v_cvt_pk_bf16_f32 v23, v23, v24
	global_store_dwordx2 v[18:19], v[22:23], off offset:1024
	v_mul_f32_e32 v22, v50, v0
	v_mul_f32_e32 v23, v51, v0
	v_mul_f32_e32 v22, v14, v22
	v_mul_f32_e32 v23, v15, v23
	v_cvt_pk_bf16_f32 v22, v22, v23
	v_mul_f32_e32 v23, v52, v0
	v_mul_f32_e32 v23, v16, v23
	v_mul_f32_e32 v0, v53, v0
	v_mul_f32_e32 v0, v17, v0
	v_cvt_pk_bf16_f32 v23, v23, v0
	global_store_dwordx2 v[18:19], v[22:23], off offset:1536
	v_lshl_add_u64 v[18:19], v[18:19], 0, s[8:9]
	s_add_i32 s6, s6, s4
	s_cmp_lt_i32 s6, 0x8000
	s_cbranch_scc1 .LBB0_338
.Lrms2_x_b:
.LBB0_339:
	s_mov_b64 s[6:7], 0
	s_getreg_b32 s8, hwreg(HW_REG_XCC_ID, 0, 4)
	s_waitcnt vmcnt(0)
	s_barrier
	s_and_saveexec_b64 s[4:5], s[84:85]
	s_cbranch_execz .LBB0_391
	v_readlane_b32 s9, v255, 21
	s_waitcnt vmcnt(0) expcnt(0) lgkmcnt(0)
	s_add_u32 s6, s94, s6
	v_mov_b32_e32 v0, s9
	ds_read_b32 v3, v0
	v_readlane_b32 s9, v255, 22
	s_addc_u32 s7, s95, s7
	s_and_b32 s52, s8, 15
	v_mov_b32_e32 v0, s9
	ds_read_b32 v2, v0
	s_waitcnt lgkmcnt(1)
	v_cmp_ne_u32_e32 vcc, 0, v3
	s_cbranch_vccnz .LBB0_355
	s_add_u32 s8, s6, 0x2f00200
	s_addc_u32 s9, s7, 0
	s_add_u32 s10, s6, 0x2f00400
	s_addc_u32 s11, s7, 0
	s_add_u32 s12, s6, 0x2f00500
	s_addc_u32 s13, s7, 0
	s_add_u32 s14, s6, 0x2f00600
	s_addc_u32 s15, s7, 0
	s_add_u32 s16, s6, 0x2f00700
	s_addc_u32 s17, s7, 0
	s_add_u32 s18, s6, 0x2f00800
	s_addc_u32 s19, s7, 0
	s_add_u32 s20, s6, 0x2f00900
	s_addc_u32 s21, s7, 0
	s_add_u32 s22, s6, 0x2f00a00
	s_addc_u32 s23, s7, 0
	s_add_u32 s24, s6, 0x2f00b00
	s_addc_u32 s25, s7, 0
	s_add_u32 s26, s6, 0x2f00c00
	s_addc_u32 s27, s7, 0
	s_add_u32 s28, s6, 0x2f00d00
	s_addc_u32 s29, s7, 0
	s_add_u32 s30, s6, 0x2f00e00
	s_addc_u32 s31, s7, 0
	s_add_u32 s34, s6, 0x2f00f00
	s_addc_u32 s35, s7, 0
	s_add_u32 s36, s6, 0x2f01000
	s_addc_u32 s37, s7, 0
	s_add_u32 s38, s6, 0x2f01100
	s_addc_u32 s39, s7, 0
	s_add_u32 s40, s6, 0x2f01200
	s_addc_u32 s41, s7, 0
	s_add_u32 s42, s6, 0x2f01300
	s_addc_u32 s43, s7, 0
	s_mov_b32 s53, 1
	s_branch .LBB0_343
